# sub-phase order diversity extended to P6: workgroups with blockIdx bit 3 run kvprep before the cross-q GEMM
# baseline (speedup 1.0000x reference)
.LBB0_1158:
	s_cmp_lt_i32 s86, 7
	s_cselect_b64 s[0:1], -1, 0
	s_cmp_gt_i32 s87, 6
	s_cselect_b64 s[2:3], -1, 0
	s_and_b64 s[0:1], s[0:1], s[2:3]
	s_andn2_b64 vcc, exec, s[0:1]
	s_cbranch_vccnz .LBB0_1240
	s_mov_b32 s94, 2
	s_bitcmp1_b32 s33, 3
	s_cbranch_scc0 .Lmy_p6_pre
	s_mov_b32 s94, 0
.Lmy_p6_pre:
	s_cmp_eq_u32 s94, 0
	s_cbranch_scc1 .LBB0_1183
	s_cmpk_gt_i32 s33, 0xff
	v_readfirstlane_b32 s6, v158
	s_cbranch_scc1 .LBB0_1183
	s_ashr_i32 s38, s33, 31
	s_lshr_b32 s0, s38, 26
	s_add_i32 s4, s33, s0
	s_and_b32 s0, s4, 0xffc0
	s_sub_i32 s0, s33, s0
	s_bfe_i32 s1, s0, 0x80000
	s_bfe_u32 s1, s1, 0x3000c
	s_add_i32 s1, s0, s1
	s_bfe_i32 s2, s1, 0x80000
	s_and_b32 s1, s1, 0xf8
	s_sub_i32 s0, s0, s1
	s_bfe_i32 s3, s0, 0x80000
	s_sext_i32_i16 s0, s3
	s_cmp_gt_i32 s0, -1
	s_sext_i32_i16 s5, s2
	s_cbranch_scc0 .LBB0_1162
	s_lshl_b32 s2, s3, 3
	s_ashr_i32 s22, s4, 6
	s_lshr_b32 s0, s5, 3
	s_cbranch_execz .LBB0_1163
	s_branch .LBB0_1164

.LBB0_1183:
	s_cmp_eq_u32 s94, 1
	s_cbranch_scc1 .Lmy_p6_done
	s_waitcnt lgkmcnt(0)
	v_lshl_add_u32 v10, s33, 3, v159
	s_movk_i32 s0, 0x1000
	v_cmp_gt_i32_e32 vcc, s0, v10
	s_and_saveexec_b64 s[0:1], vcc
	s_cbranch_execz .LBB0_1186
	v_mbcnt_lo_u32_b32 v2, -1, 0
	v_mbcnt_hi_u32_b32 v2, -1, v2
	v_and_b32_e32 v3, 64, v2
	v_add_u32_e32 v3, 64, v3
	v_xor_b32_e32 v4, 1, v2
	v_cmp_lt_i32_e32 vcc, v4, v3
	v_lshlrev_b32_e32 v0, 1, v158
	v_and_b32_e32 v8, 0x7e, v0
	v_cndmask_b32_e32 v4, v2, v4, vcc
	v_lshlrev_b32_e32 v11, 2, v4
	v_xor_b32_e32 v4, 2, v2
	v_cmp_lt_i32_e32 vcc, v4, v3
	v_readlane_b32 s12, v252, 23
	v_mov_b32_e32 v1, 0
	v_cndmask_b32_e32 v4, v2, v4, vcc
	v_lshlrev_b32_e32 v12, 2, v4
	v_xor_b32_e32 v4, 4, v2
	v_cmp_lt_i32_e32 vcc, v4, v3
	v_lshlrev_b32_e32 v0, 2, v8
	v_readlane_b32 s20, v252, 31
	v_cndmask_b32_e32 v4, v2, v4, vcc
	v_lshlrev_b32_e32 v13, 2, v4
	v_xor_b32_e32 v4, 8, v2
	v_cmp_lt_i32_e32 vcc, v4, v3
	v_readlane_b32 s21, v252, 32
	s_add_u32 s2, s84, 0x5088000
	v_cndmask_b32_e32 v4, v2, v4, vcc
	v_lshlrev_b32_e32 v14, 2, v4
	v_xor_b32_e32 v4, 16, v2
	v_cmp_lt_i32_e32 vcc, v4, v3
	v_lshl_add_u64 v[6:7], s[84:85], 0, v[0:1]
	v_bfe_u32 v17, v158, 6, 2
	v_cndmask_b32_e32 v4, v2, v4, vcc
	v_lshlrev_b32_e32 v15, 2, v4
	v_xor_b32_e32 v4, 32, v2
	v_cmp_lt_i32_e32 vcc, v4, v3
	s_addc_u32 s3, s85, 0
	s_mov_b64 s[6:7], 0x5800000
	v_cndmask_b32_e32 v2, v2, v4, vcc
	v_lshlrev_b32_e32 v16, 2, v2
	v_lshl_add_u64 v[2:3], s[20:21], 0, v[0:1]
	v_lshlrev_b32_e32 v0, 9, v8
	v_lshl_add_u64 v[4:5], s[84:85], 0, v[0:1]
	v_lshlrev_b32_e32 v0, 9, v17
	s_add_u32 s4, s84, 0x5700000
	v_lshl_add_u64 v[4:5], v[4:5], 0, s[6:7]
	v_lshl_add_u64 v[6:7], v[6:7], 0, v[0:1]
	s_mov_b64 s[6:7], 0x8c00000
	s_addc_u32 s5, s85, 0
	s_lshl_b32 s8, s88, 3
	v_lshl_add_u64 v[6:7], v[6:7], 0, s[6:7]
	s_mov_b64 s[6:7], 0
	v_mov_b32_e32 v18, 0x358637bd
	s_mov_b32 s9, 0x800000
	v_lshlrev_b32_e32 v8, 1, v8
	v_mov_b32_e32 v9, v1
	s_movk_i32 s10, 0x7fff
	s_movk_i32 s11, 0xfff
	v_mov_b32_e32 v19, 8
	v_mov_b32_e32 v20, 1
	v_readlane_b32 s13, v252, 24
	v_readlane_b32 s14, v252, 25
	v_readlane_b32 s15, v252, 26
	v_readlane_b32 s16, v252, 27
	v_readlane_b32 s17, v252, 28
	v_readlane_b32 s18, v252, 29
	v_readlane_b32 s19, v252, 30
	v_readlane_b32 s22, v252, 33
	v_readlane_b32 s23, v252, 34
	v_readlane_b32 s24, v252, 35
	v_readlane_b32 s25, v252, 36
	v_readlane_b32 s26, v252, 37
	v_readlane_b32 s27, v252, 38

.LBB0_1186:
	s_or_b64 exec, exec, s[0:1]
	s_cmp_eq_u32 s94, 0
	s_cbranch_scc0 .Lmy_p6_done
	s_mov_b32 s94, 1
	s_waitcnt vmcnt(0) lgkmcnt(0)
	s_branch .Lmy_p6_pre
.Lmy_p6_done:
	s_cmp_lt_i32 s87, 8
	s_cbranch_scc1 .LBB0_1240
	s_waitcnt vmcnt(0)
	s_waitcnt vmcnt(0)
	s_barrier
	s_mov_b64 s[0:1], exec
	v_readlane_b32 s2, v252, 5
	v_readlane_b32 s3, v252, 6
	s_and_b64 s[2:3], s[0:1], s[2:3]
	s_mov_b64 exec, s[2:3]
	s_cbranch_execz .LBB0_1239
	s_add_i32 s2, 0, 0x25fc0
	v_mov_b32_e32 v0, s2
	s_waitcnt vmcnt(0) expcnt(0) lgkmcnt(0)
	ds_read_b32 v2, v0
	s_add_i32 s2, 0, 0x25fc4
	v_mov_b32_e32 v0, s2
	ds_read_b32 v0, v0
	s_waitcnt lgkmcnt(1)
	v_cmp_ne_u32_e32 vcc, 0, v2
	s_cbranch_vccnz .LBB0_1203
	v_readlane_b32 s2, v252, 0
	v_readlane_b32 s3, v252, 1
	s_load_dwordx2 s[6:7], s[2:3], 0x4
	s_add_u32 s2, s84, 0x5900200
	s_addc_u32 s3, s85, 0
	s_add_u32 s4, s84, 0x5900400
	s_addc_u32 s5, s85, 0
	s_waitcnt lgkmcnt(0)
	s_mul_i32 s44, s6, s88
	s_add_u32 s6, s84, 0x5900500
	s_mul_i32 s44, s44, s7
	s_addc_u32 s7, s85, 0
	s_add_u32 s8, s84, 0x5900600
	s_addc_u32 s9, s85, 0
	s_add_u32 s10, s84, 0x5900700
	s_addc_u32 s11, s85, 0
	s_add_u32 s12, s84, 0x5900800
	s_addc_u32 s13, s85, 0
	s_add_u32 s14, s84, 0x5900900
	s_addc_u32 s15, s85, 0
	s_add_u32 s16, s84, 0x5900a00
	s_addc_u32 s17, s85, 0
	s_add_u32 s18, s84, 0x5900b00
	s_addc_u32 s19, s85, 0
	s_add_u32 s20, s84, 0x5900c00
	s_addc_u32 s21, s85, 0
	s_add_u32 s22, s84, 0x5900d00
	s_addc_u32 s23, s85, 0
	s_add_u32 s24, s84, 0x5900e00
	s_addc_u32 s25, s85, 0
	s_add_u32 s26, s84, 0x5900f00
	s_addc_u32 s27, s85, 0
	s_add_u32 s28, s84, 0x5901000
	s_addc_u32 s29, s85, 0
	s_add_u32 s30, s84, 0x5901100
	s_addc_u32 s31, s85, 0
	s_add_u32 s34, s84, 0x5901200
	s_addc_u32 s35, s85, 0
	s_add_u32 s36, s84, 0x5901300
	s_addc_u32 s37, s85, 0
	s_mov_b32 s45, 1
	v_mov_b32_e32 v16, 0
	s_branch .LBB0_1191
